# attention hot-loop heads aligned to 64 bytes (placement pin); includes DPP gate preambles in m1 and m3
# speedup vs baseline: 1.0136x; 1.0136x over previous
.LBB0_505:
	v_add_f32_e32 v16, 0, v32
	v_add_f32_e32 v16, v33, v16
	v_add_f32_e32 v17, 0, v40
	v_add_f32_e32 v16, v34, v16
	v_add_f32_e32 v17, v41, v17
	v_add_f32_e32 v16, v35, v16
	v_add_f32_e32 v17, v42, v17
	v_add_f32_e32 v16, v36, v16
	v_add_f32_e32 v17, v43, v17
	v_add_f32_e32 v16, v37, v16
	v_add_f32_e32 v17, v44, v17
	v_add_f32_e32 v16, v38, v16
	v_add_f32_e32 v17, v45, v17
	v_add_f32_e32 v16, v39, v16
	v_add_f32_e32 v17, v46, v17
	v_add_f32_e32 v16, 0, v16
	v_add_f32_e32 v17, v47, v17
	v_add_f32_e32 v18, 0, v48
	v_add_f32_e32 v16, v17, v16
	v_add_f32_e32 v17, 0, v56
	v_add_f32_e32 v18, v49, v18
	v_add_f32_e32 v17, v57, v17
	v_add_f32_e32 v18, v50, v18
	v_add_f32_e32 v17, v58, v17
	v_add_f32_e32 v18, v51, v18
	v_add_f32_e32 v17, v59, v17
	v_add_f32_e32 v18, v52, v18
	v_add_f32_e32 v17, v60, v17
	v_add_f32_e32 v18, v53, v18
	v_add_f32_e32 v17, v61, v17
	v_add_f32_e32 v18, v54, v18
	s_waitcnt vmcnt(0)
	ds_write_b64 v216, v[64:65] offset:18432
	s_waitcnt lgkmcnt(0)
	ds_write_b64 v216, v[68:69] offset:27648
	ds_write2st64_b64 v217, v[66:67], v[70:71] offset0:36 offset1:54
	ds_write_b128 v213, v[144:147]
	v_add_f32_e32 v17, v62, v17
	v_add_f32_e32 v18, v55, v18
	s_waitcnt lgkmcnt(0)
	s_barrier
	v_add_f32_e32 v17, v63, v17
	v_add_f32_e32 v16, v18, v16
	v_mov_b32_e32 v31, 0
	v_cvt_pk_bf16_f32 v160, v32, v33
	v_cvt_pk_bf16_f32 v161, v34, v35
	v_cvt_pk_bf16_f32 v162, v36, v37
	v_cvt_pk_bf16_f32 v163, v38, v39
	v_cvt_pk_bf16_f32 v148, v40, v41
	v_cvt_pk_bf16_f32 v149, v42, v43
	v_cvt_pk_bf16_f32 v150, v44, v45
	v_cvt_pk_bf16_f32 v151, v46, v47
	v_cvt_pk_bf16_f32 v152, v48, v49
	v_cvt_pk_bf16_f32 v153, v50, v51
	v_cvt_pk_bf16_f32 v154, v52, v53
	v_cvt_pk_bf16_f32 v155, v54, v55
	v_add_f32_e32 v193, v17, v16
	v_cvt_pk_bf16_f32 v156, v56, v57
	v_cvt_pk_bf16_f32 v157, v58, v59
	v_cvt_pk_bf16_f32 v158, v60, v61
	v_cvt_pk_bf16_f32 v159, v62, v63
	s_andn2_b64 vcc, exec, s[2:3]
	s_cbranch_vccnz .LBB0_512
	v_mov_b32_e32 v32, 0
	s_mov_b32 s93, 0
	s_movk_i32 s15, 0x80
	s_mov_b64 s[6:7], 0x80
	v_mov_b32_e32 v33, v32
	v_mov_b32_e32 v34, v32
	v_mov_b32_e32 v35, v32
	v_mov_b32_e32 v36, v32
	v_mov_b32_e32 v37, v32
	v_mov_b32_e32 v38, v32
	v_mov_b32_e32 v39, v32
	v_mov_b32_e32 v40, v32
	v_mov_b32_e32 v41, v32
	v_mov_b32_e32 v42, v32
	v_mov_b32_e32 v43, v32
	v_mov_b32_e32 v44, v32
	v_mov_b32_e32 v45, v32
	v_mov_b32_e32 v46, v32
	v_mov_b32_e32 v47, v32
	v_mov_b32_e32 v64, v32
	v_mov_b32_e32 v65, v32
	v_mov_b32_e32 v66, v32
	v_mov_b32_e32 v67, v32
	v_mov_b32_e32 v68, v32
	v_mov_b32_e32 v69, v32
	v_mov_b32_e32 v70, v32
	v_mov_b32_e32 v71, v32
	v_mov_b32_e32 v72, v32
	v_mov_b32_e32 v73, v32
	v_mov_b32_e32 v74, v32
	v_mov_b32_e32 v75, v32
	v_mov_b32_e32 v76, v32
	v_mov_b32_e32 v77, v32
	v_mov_b32_e32 v78, v32
	v_mov_b32_e32 v79, v32
	v_mov_b32_e32 v48, v32
	v_mov_b32_e32 v49, v32
	v_mov_b32_e32 v50, v32
	v_mov_b32_e32 v51, v32
	v_mov_b32_e32 v52, v32
	v_mov_b32_e32 v53, v32
	v_mov_b32_e32 v54, v32
	v_mov_b32_e32 v55, v32
	v_mov_b32_e32 v56, v32
	v_mov_b32_e32 v57, v32
	v_mov_b32_e32 v58, v32
	v_mov_b32_e32 v59, v32
	v_mov_b32_e32 v60, v32
	v_mov_b32_e32 v61, v32
	v_mov_b32_e32 v62, v32
	v_mov_b32_e32 v63, v32
	v_mov_b32_e32 v16, v32
	v_mov_b32_e32 v17, v32
	v_mov_b32_e32 v18, v32
	v_mov_b32_e32 v19, v32
	v_mov_b32_e32 v20, v32
	v_mov_b32_e32 v21, v32
	v_mov_b32_e32 v22, v32
	v_mov_b32_e32 v23, v32
	v_mov_b32_e32 v24, v32
	v_mov_b32_e32 v25, v32
	v_mov_b32_e32 v26, v32
	v_mov_b32_e32 v27, v32
	v_mov_b32_e32 v28, v32
	v_mov_b32_e32 v29, v32
	v_mov_b32_e32 v30, v32
	v_mov_b32_e32 v31, v32
	v_mov_b32_e32 v142, 0
	s_branch .LBB0_508
	.p2align 6

.LBB0_539:
	v_add_f32_e32 v16, 0, v32
	v_add_f32_e32 v16, v33, v16
	v_add_f32_e32 v17, 0, v40
	v_add_f32_e32 v16, v34, v16
	v_add_f32_e32 v17, v41, v17
	v_add_f32_e32 v16, v35, v16
	v_add_f32_e32 v17, v42, v17
	v_add_f32_e32 v16, v36, v16
	v_add_f32_e32 v17, v43, v17
	v_add_f32_e32 v16, v37, v16
	v_add_f32_e32 v17, v44, v17
	v_add_f32_e32 v16, v38, v16
	v_add_f32_e32 v17, v45, v17
	v_add_f32_e32 v16, v39, v16
	v_add_f32_e32 v17, v46, v17
	v_add_f32_e32 v16, 0, v16
	v_add_f32_e32 v17, v47, v17
	v_add_f32_e32 v18, 0, v48
	v_add_f32_e32 v16, v17, v16
	v_add_f32_e32 v17, 0, v56
	v_add_f32_e32 v18, v49, v18
	v_add_f32_e32 v17, v57, v17
	v_add_f32_e32 v18, v50, v18
	v_add_f32_e32 v17, v58, v17
	v_add_f32_e32 v18, v51, v18
	v_add_f32_e32 v17, v59, v17
	v_add_f32_e32 v18, v52, v18
	v_add_f32_e32 v17, v60, v17
	v_add_f32_e32 v18, v53, v18
	v_add_f32_e32 v17, v61, v17
	v_add_f32_e32 v18, v54, v18
	s_waitcnt vmcnt(0)
	ds_write_b64 v216, v[64:65] offset:18432
	s_waitcnt lgkmcnt(0)
	ds_write_b64 v216, v[68:69] offset:27648
	ds_write2st64_b64 v217, v[66:67], v[70:71] offset0:36 offset1:54
	ds_write_b128 v213, v[144:147]
	v_add_f32_e32 v17, v62, v17
	v_add_f32_e32 v18, v55, v18
	s_waitcnt lgkmcnt(0)
	s_barrier
	v_add_f32_e32 v17, v63, v17
	v_add_f32_e32 v16, v18, v16
	v_mov_b32_e32 v31, 0
	v_cvt_pk_bf16_f32 v160, v32, v33
	v_cvt_pk_bf16_f32 v161, v34, v35
	v_cvt_pk_bf16_f32 v162, v36, v37
	v_cvt_pk_bf16_f32 v163, v38, v39
	v_cvt_pk_bf16_f32 v148, v40, v41
	v_cvt_pk_bf16_f32 v149, v42, v43
	v_cvt_pk_bf16_f32 v150, v44, v45
	v_cvt_pk_bf16_f32 v151, v46, v47
	v_cvt_pk_bf16_f32 v152, v48, v49
	v_cvt_pk_bf16_f32 v153, v50, v51
	v_cvt_pk_bf16_f32 v154, v52, v53
	v_cvt_pk_bf16_f32 v155, v54, v55
	v_add_f32_e32 v193, v17, v16
	v_cvt_pk_bf16_f32 v156, v56, v57
	v_cvt_pk_bf16_f32 v157, v58, v59
	v_cvt_pk_bf16_f32 v158, v60, v61
	v_cvt_pk_bf16_f32 v159, v62, v63
	s_andn2_b64 vcc, exec, s[80:81]
	s_cbranch_vccnz .LBB0_546
	v_mov_b32_e32 v32, 0
	s_mov_b32 s77, 0
	s_movk_i32 s15, 0x80
	s_mov_b64 s[6:7], 0x80
	v_mov_b32_e32 v33, v32
	v_mov_b32_e32 v34, v32
	v_mov_b32_e32 v35, v32
	v_mov_b32_e32 v36, v32
	v_mov_b32_e32 v37, v32
	v_mov_b32_e32 v38, v32
	v_mov_b32_e32 v39, v32
	v_mov_b32_e32 v40, v32
	v_mov_b32_e32 v41, v32
	v_mov_b32_e32 v42, v32
	v_mov_b32_e32 v43, v32
	v_mov_b32_e32 v44, v32
	v_mov_b32_e32 v45, v32
	v_mov_b32_e32 v46, v32
	v_mov_b32_e32 v47, v32
	v_mov_b32_e32 v64, v32
	v_mov_b32_e32 v65, v32
	v_mov_b32_e32 v66, v32
	v_mov_b32_e32 v67, v32
	v_mov_b32_e32 v68, v32
	v_mov_b32_e32 v69, v32
	v_mov_b32_e32 v70, v32
	v_mov_b32_e32 v71, v32
	v_mov_b32_e32 v72, v32
	v_mov_b32_e32 v73, v32
	v_mov_b32_e32 v74, v32
	v_mov_b32_e32 v75, v32
	v_mov_b32_e32 v76, v32
	v_mov_b32_e32 v77, v32
	v_mov_b32_e32 v78, v32
	v_mov_b32_e32 v79, v32
	v_mov_b32_e32 v48, v32
	v_mov_b32_e32 v49, v32
	v_mov_b32_e32 v50, v32
	v_mov_b32_e32 v51, v32
	v_mov_b32_e32 v52, v32
	v_mov_b32_e32 v53, v32
	v_mov_b32_e32 v54, v32
	v_mov_b32_e32 v55, v32
	v_mov_b32_e32 v56, v32
	v_mov_b32_e32 v57, v32
	v_mov_b32_e32 v58, v32
	v_mov_b32_e32 v59, v32
	v_mov_b32_e32 v60, v32
	v_mov_b32_e32 v61, v32
	v_mov_b32_e32 v62, v32
	v_mov_b32_e32 v63, v32
	v_mov_b32_e32 v16, v32
	v_mov_b32_e32 v17, v32
	v_mov_b32_e32 v18, v32
	v_mov_b32_e32 v19, v32
	v_mov_b32_e32 v20, v32
	v_mov_b32_e32 v21, v32
	v_mov_b32_e32 v22, v32
	v_mov_b32_e32 v23, v32
	v_mov_b32_e32 v24, v32
	v_mov_b32_e32 v25, v32
	v_mov_b32_e32 v26, v32
	v_mov_b32_e32 v27, v32
	v_mov_b32_e32 v28, v32
	v_mov_b32_e32 v29, v32
	v_mov_b32_e32 v30, v32
	v_mov_b32_e32 v31, v32
	v_mov_b32_e32 v142, 0
	s_branch .LBB0_542
	.p2align 6
